# RWKV layer LN1->up: group wait + control-only check that every group left the out-projection (no cache maintenance) instead of the grid barrier
# speedup vs baseline: 1.0166x; 1.0003x over previous
.Lmy_gchk_3:
	s_mov_b32 s2, -1
	s_nop 0
	v_mbcnt_lo_u32_b32 v0, s2, 0
	v_mbcnt_hi_u32_b32 v0, s2, v0
	s_nop 0
	v_cmp_eq_u32_e32 vcc, 0, v0
	s_and_saveexec_b64 s[16:17], vcc
	s_cbranch_execz .LBB0_2032
	s_cmp_lg_u32 s101, 1
	s_cbranch_scc1 .Lmy_gfull_3
	v_readlane_b32 s100, v253, 37
	v_readlane_b32 s3, v250, 7
	v_readlane_b32 s8, v250, 0
	v_readlane_b32 s9, v250, 1
	s_lshl_b32 s12, s100, 11
	s_add_i32 s2, s12, 0x3000
	s_and_b32 s13, s3, 63
	s_lshl_b32 s13, s13, 6
	s_add_i32 s2, s2, s13
	s_add_u32 s8, s8, 0x70000
	s_addc_u32 s9, s9, 0
	v_mov_b32_e32 v0, s2
	v_mov_b32_e32 v1, 1
	s_waitcnt vmcnt(0) lgkmcnt(0)
	global_atomic_add v0, v1, s[8:9]
	s_mov_b32 s2, 0
.Lmy_gspin_3:
	global_load_dword v2, v0, s[8:9] sc1
	s_waitcnt vmcnt(0)
	v_readfirstlane_b32 s13, v2
	s_cmp_ge_u32 s13, 4
	s_cbranch_scc1 .Lmy_g3_own
	s_sleep 1
	s_add_i32 s2, s2, 1
	s_cmp_lt_u32 s2, 0x4000
	s_cbranch_scc1 .Lmy_gspin_3
.Lmy_g3_own:
	s_cmp_lg_u32 s100, 32
	s_cbranch_scc1 .Lmy_gdone_3
	s_mov_b64 exec, -1
	s_mov_b32 s2, -1
	v_mbcnt_lo_u32_b32 v0, s2, 0
	v_mbcnt_hi_u32_b32 v0, s2, v0
	v_lshlrev_b32_e32 v0, 6, v0
	v_add_u32_e32 v0, s12, v0
	s_mov_b32 s100, 0
.Lmy_g3_pspin:
	global_load_dword v2, v0, s[8:9] sc1
	s_waitcnt vmcnt(0)
	v_cmp_gt_u32_e32 vcc, 4, v2
	s_cmp_eq_u64 vcc, 0
	s_cbranch_scc1 .Lmy_gdone_3
	s_sleep 8
	s_add_i32 s100, s100, 1
	s_cmp_lt_u32 s100, 0x1000
	s_cbranch_scc1 .Lmy_g3_pspin
